# Fm DFT table: one sincospif per (s,t) feeds both the cos row and the sin row (halves the table's VALU work), on top of K-split + QK fusion
# speedup vs baseline: 1.0027x; 1.0027x over previous
; __device__ __forceinline__ u32x4 pack8(const f32x4 a, const f32x4 b) { u32x4 w; w.x = cvt_pk_bf16(a[0], a[1]); w.y = cvt_pk_bf16(a[2], a[3]); w.z = cvt_pk_bf16(b[0], b[1]); w.w = cvt_pk_bf16(b[2], b[3]); return w; }
; __device__ void ph_prep(const Params& p, LAS unsigned char* lds_in, const int WID) {
;     ...
;     bf16_t* Fm = (bf16_t*)(p.ws + OFF_FM);
;     for (int it = blockIdx.x * NTHREADS + tid; it < 4096 * 256; it += gridDim.x * NTHREADS) {
;         const int row = it >> 8, t0 = (it & 255) * 8, s = row & 2047, part = row >> 11;
;         f32x4 a, b;
; #pragma unroll
;         for (int j = 0; j < 8; ++j) { float sn, cs; sincospif((float)((s * (t0 + j)) & 2047) / 1024.0f, &sn, &cs); const float v = (part ? sn : cs) * 0.022097086912079608f; if (j < 4) a[j] = v; else b[j - 4] = v; }
;         *(u32x4*)(Fm + (size_t)row * 2048 + t0) = pack8(a, b);
;     }
.LBB0_110:
	s_add_u32 s76, s92, 0xf800000
	s_addc_u32 s77, s93, 0
	s_lshl_b32 s84, s90, 9
	v_add_u32_e32 v8, s84, v50
	s_mov_b32 s0, 0x100000
	v_cmp_gt_i32_e32 vcc, s0, v8
	s_and_saveexec_b64 s[16:17], vcc
	s_cbranch_execz .LBB0_113
	v_lshlrev_b32_e32 v2, 3, v50
	s_lshl_b32 s21, s91, 9
	v_lshl_add_u32 v9, s90, 12, v2
	s_lshl_b32 s22, s91, 12
	s_mov_b64 s[18:19], 0
	s_mov_b32 s23, 0x80000
	s_mov_b32 s20, 0x3a800000
	s_mov_b32 s25, 0x7f800000
	v_mov_b32_e32 v10, 0x3e642e9d
	v_mov_b32_e32 v11, 0xbf1f24be
	s_brev_b32 s26, 1
	v_mov_b32_e32 v12, 0x7fc00000
	v_mov_b32_e32 v3, 0
	s_mov_b32 s27, 0x7ffff
.LBB0_112:
	v_ashrrev_i32_e32 v4, 8, v8
	v_or_b32_e32 v2, 2, v9
	v_or_b32_e32 v5, 3, v9
	v_or_b32_e32 v6, 4, v9
	v_or_b32_e32 v7, 5, v9
	v_or_b32_e32 v13, 6, v9
	v_or_b32_e32 v14, 7, v9
	v_and_b32_e32 v15, 0x7f8, v9
	v_mul_lo_u32 v16, v9, v4
	v_mul_lo_u32 v17, v2, v4
	v_mul_lo_u32 v18, v5, v4
	v_mul_lo_u32 v6, v6, v4
	v_mul_lo_u32 v7, v7, v4
	v_mul_lo_u32 v13, v13, v4
	v_mul_lo_u32 v14, v14, v4
	v_lshlrev_b32_e32 v2, 1, v15
	v_add_u32_e32 v15, v16, v4
	v_and_b32_e32 v17, 0x7fe, v17
	v_and_b32_e32 v18, 0x7ff, v18
	v_and_b32_e32 v16, 0x7f8, v16
	v_and_b32_e32 v6, 0x7fc, v6
	v_and_b32_e32 v19, 0x7ff, v7
	v_and_b32_e32 v13, 0x7fe, v13
	v_and_b32_e32 v20, 0x7ff, v14
	v_and_b32_e32 v21, 0x7ff, v15
	v_cvt_f32_u32_e32 v15, v17
	v_cvt_f32_u32_e32 v14, v18
	v_cvt_f32_u32_e32 v7, v16
	v_cvt_f32_u32_e32 v17, v6
	v_cvt_f32_u32_e32 v16, v19
	v_cvt_f32_u32_e32 v19, v13
	v_cvt_f32_u32_e32 v18, v20
	v_cvt_f32_u32_e32 v6, v21
	v_ashrrev_i32_e32 v5, 31, v4
	v_lshlrev_b64 v[4:5], 12, v[4:5]
	v_pk_mul_f32 v[14:15], v[14:15], s[20:21] op_sel_hi:[1,0]
	v_lshl_add_u64 v[4:5], s[76:77], 0, v[4:5]
	v_pk_mul_f32 v[16:17], v[16:17], s[20:21] op_sel_hi:[1,0]
	v_pk_mul_f32 v[18:19], v[18:19], s[20:21] op_sel_hi:[1,0]
	v_pk_mul_f32 v[6:7], v[6:7], s[20:21] op_sel_hi:[1,0]
	v_pk_mul_f32 v[20:21], v[14:15], 0.5 op_sel_hi:[1,0]
	v_lshl_add_u64 v[4:5], v[4:5], 0, v[2:3]
	v_pk_mul_f32 v[22:23], v[16:17], 0.5 op_sel_hi:[1,0]
	v_pk_mul_f32 v[24:25], v[18:19], 0.5 op_sel_hi:[1,0]
	v_pk_mul_f32 v[26:27], v[6:7], 0.5 op_sel_hi:[1,0]
	v_fract_f32_e32 v2, v21
	v_fract_f32_e32 v13, v20
	v_fract_f32_e32 v28, v23
	v_fract_f32_e32 v29, v22
	v_fract_f32_e32 v30, v25
	v_fract_f32_e32 v31, v24
	v_fract_f32_e32 v32, v27
	v_fract_f32_e32 v33, v26
	v_add_f32_e32 v2, v2, v2
	v_cmp_neq_f32_e32 vcc, s25, v21
	v_add_f32_e32 v13, v13, v13
	v_cmp_neq_f32_e64 s[0:1], s25, v20
	v_add_f32_e32 v20, v28, v28
	v_cmp_neq_f32_e64 s[4:5], s25, v23
	v_add_f32_e32 v21, v29, v29
	v_cmp_neq_f32_e64 s[6:7], s25, v22
	v_add_f32_e32 v22, v30, v30
	v_cmp_neq_f32_e64 s[8:9], s25, v25
	v_add_f32_e32 v23, v31, v31
	v_cmp_neq_f32_e64 s[10:11], s25, v24
	v_add_f32_e32 v24, v32, v32
	v_add_f32_e32 v25, v33, v33
	v_cmp_neq_f32_e64 s[12:13], s25, v26
	v_cndmask_b32_e32 v2, 0, v2, vcc
	v_cmp_lt_f32_e32 vcc, 1.0, v15
	v_cmp_neq_f32_e64 s[14:15], s25, v27
	v_cndmask_b32_e64 v13, 0, v13, s[0:1]
	v_cmp_lt_f32_e64 s[0:1], 1.0, v14
	v_cndmask_b32_e64 v20, 0, v20, s[4:5]
	v_cmp_lt_f32_e64 s[4:5], 1.0, v17
	v_cndmask_b32_e64 v21, 0, v21, s[6:7]
	v_cmp_lt_f32_e64 s[6:7], 1.0, v16
	v_cndmask_b32_e64 v22, 0, v22, s[8:9]
	v_cmp_lt_f32_e64 s[8:9], 1.0, v19
	v_cndmask_b32_e64 v23, 0, v23, s[10:11]
	v_cmp_lt_f32_e64 s[10:11], 1.0, v18
	v_cndmask_b32_e64 v24, 0, v24, s[14:15]
	v_cndmask_b32_e64 v25, 0, v25, s[12:13]
	v_cmp_lt_f32_e64 s[12:13], 1.0, v6
	v_cndmask_b32_e32 v2, v15, v2, vcc
	v_cmp_lt_f32_e32 vcc, 1.0, v7
	v_cndmask_b32_e64 v13, v14, v13, s[0:1]
	v_cndmask_b32_e64 v20, v17, v20, s[4:5]
	v_cndmask_b32_e64 v21, v16, v21, s[6:7]
	v_cndmask_b32_e64 v22, v19, v22, s[8:9]
	v_cndmask_b32_e64 v23, v18, v23, s[10:11]
	v_cndmask_b32_e32 v24, v7, v24, vcc
	v_cndmask_b32_e64 v25, v6, v25, s[12:13]
	v_add_f32_e32 v26, v2, v2
	v_add_f32_e32 v27, v13, v13
	v_add_f32_e32 v28, v20, v20
	v_add_f32_e32 v29, v21, v21
	v_add_f32_e32 v30, v22, v22
	v_add_f32_e32 v31, v23, v23
	v_add_f32_e32 v32, v24, v24
	v_add_f32_e32 v33, v25, v25
	v_rndne_f32_e32 v26, v26
	v_rndne_f32_e32 v27, v27
	v_rndne_f32_e32 v28, v28
	v_rndne_f32_e32 v29, v29
	v_rndne_f32_e32 v30, v30
	v_rndne_f32_e32 v31, v31
	v_rndne_f32_e32 v32, v32
	v_rndne_f32_e32 v33, v33
	v_fmac_f32_e32 v2, -0.5, v26
	v_cvt_i32_f32_e32 v34, v26
	v_cvt_i32_f32_e32 v26, v27
	v_fmac_f32_e32 v13, -0.5, v27
	v_cvt_i32_f32_e32 v27, v28
	v_fmac_f32_e32 v20, -0.5, v28
	v_cvt_i32_f32_e32 v28, v29
	v_fmac_f32_e32 v21, -0.5, v29
	v_cvt_i32_f32_e32 v29, v30
	v_fmac_f32_e32 v22, -0.5, v30
	v_cvt_i32_f32_e32 v30, v31
	v_fmac_f32_e32 v23, -0.5, v31
	v_cvt_i32_f32_e32 v31, v32
	v_fmac_f32_e32 v24, -0.5, v32
	v_cvt_i32_f32_e32 v32, v33
	v_fmac_f32_e32 v25, -0.5, v33
	v_mul_f32_e32 v33, v2, v2
	v_mul_f32_e32 v35, v13, v13
	v_mul_f32_e32 v36, v20, v20
	v_mul_f32_e32 v37, v21, v21
	v_mul_f32_e32 v38, v22, v22
	v_mul_f32_e32 v39, v23, v23
	v_mul_f32_e32 v40, v24, v24
	v_mul_f32_e32 v41, v25, v25
	v_fmamk_f32 v44, v33, 0x3e75aa41, v11
	v_fmamk_f32 v42, v33, 0x3d4be544, v10
	v_fmamk_f32 v45, v35, 0x3d4be544, v10
	v_fmamk_f32 v47, v35, 0x3e75aa41, v11
	v_fmamk_f32 v48, v36, 0x3d4be544, v10
	v_fmamk_f32 v50, v36, 0x3e75aa41, v11
	v_fmamk_f32 v51, v37, 0x3d4be544, v10
	v_fmamk_f32 v53, v37, 0x3e75aa41, v11
	v_fmamk_f32 v56, v38, 0x3e75aa41, v11
	v_fmamk_f32 v57, v39, 0x3d4be544, v10
	v_fmamk_f32 v59, v39, 0x3e75aa41, v11
	v_fmamk_f32 v62, v40, 0x3e75aa41, v11
	v_fmamk_f32 v65, v41, 0x3e75aa41, v11
	v_fmaak_f32 v44, v33, v44, 0x40234736
	v_mul_f32_e32 v43, v2, v33
	v_fmamk_f32 v54, v38, 0x3d4be544, v10
	v_fmamk_f32 v60, v40, 0x3d4be544, v10
	v_fmamk_f32 v63, v41, 0x3d4be544, v10
	v_fmaak_f32 v42, v33, v42, 0xbfaad1da
; __device__ __forceinline__ u32x4 pack8(const f32x4 a, const f32x4 b) { u32x4 w; w.x = cvt_pk_bf16(a[0], a[1]); w.y = cvt_pk_bf16(a[2], a[3]); w.z = cvt_pk_bf16(b[0], b[1]); w.w = cvt_pk_bf16(b[2], b[3]); return w; }
; __device__ void ph_prep(const Params& p, LAS unsigned char* lds_in, const int WID) {
;     ...
;         const int row = it >> 8, t0 = (it & 255) * 8, s = row & 2047, part = row >> 11;
;         f32x4 a, b;
; #pragma unroll
;         for (int j = 0; j < 8; ++j) { float sn, cs; sincospif((float)((s * (t0 + j)) & 2047) / 1024.0f, &sn, &cs); const float v = (part ? sn : cs) * 0.022097086912079608f; if (j < 4) a[j] = v; else b[j - 4] = v; }
;         *(u32x4*)(Fm + (size_t)row * 2048 + t0) = pack8(a, b);
	v_fmaak_f32 v45, v35, v45, 0xbfaad1da
	v_fmaak_f32 v47, v35, v47, 0x40234736
	v_fmaak_f32 v48, v36, v48, 0xbfaad1da
	v_fmaak_f32 v50, v36, v50, 0x40234736
	v_fmaak_f32 v51, v37, v51, 0xbfaad1da
	v_fmaak_f32 v53, v37, v53, 0x40234736
	v_fmaak_f32 v56, v38, v56, 0x40234736
	v_fmaak_f32 v57, v39, v57, 0xbfaad1da
	v_fmaak_f32 v59, v39, v59, 0x40234736
	v_fmaak_f32 v62, v40, v62, 0x40234736
	v_fmaak_f32 v65, v41, v65, 0x40234736
	v_fmaak_f32 v44, v33, v44, 0xc0a55e0e
	v_mul_f32_e32 v46, v13, v35
	v_mul_f32_e32 v49, v20, v36
	v_mul_f32_e32 v52, v21, v37
	v_mul_f32_e32 v55, v22, v38
	v_mul_f32_e32 v58, v23, v39
	v_mul_f32_e32 v61, v24, v40
	v_mul_f32_e32 v64, v25, v41
	v_fmaak_f32 v54, v38, v54, 0xbfaad1da
	v_fmaak_f32 v60, v40, v60, 0xbfaad1da
	v_fmaak_f32 v63, v41, v63, 0xbfaad1da
	v_fmaak_f32 v42, v33, v42, 0x4081e0d3
	v_fmaak_f32 v45, v35, v45, 0x4081e0d3
	v_fmaak_f32 v47, v35, v47, 0xc0a55e0e
	v_fmaak_f32 v48, v36, v48, 0x4081e0d3
	v_fmaak_f32 v50, v36, v50, 0xc0a55e0e
	v_fmaak_f32 v51, v37, v51, 0x4081e0d3
	v_fmaak_f32 v53, v37, v53, 0xc0a55e0e
	v_fmaak_f32 v56, v38, v56, 0xc0a55e0e
	v_fmaak_f32 v57, v39, v57, 0x4081e0d3
	v_fmaak_f32 v59, v39, v59, 0xc0a55e0e
	v_fmaak_f32 v62, v40, v62, 0xc0a55e0e
	v_fmaak_f32 v65, v41, v65, 0xc0a55e0e
	v_mul_f32_e32 v43, v43, v44
	v_and_b32_e32 v66, 1, v34
	v_fmaak_f32 v54, v38, v54, 0x4081e0d3
	v_fmaak_f32 v60, v40, v60, 0x4081e0d3
	v_fmaak_f32 v63, v41, v63, 0x4081e0d3
	v_fmaak_f32 v42, v33, v42, 0xc09de9e6
	v_fmaak_f32 v44, v35, v45, 0xc09de9e6
	v_mul_f32_e32 v45, v46, v47
	v_fmaak_f32 v46, v36, v48, 0xc09de9e6
	v_mul_f32_e32 v47, v49, v50
	v_fmaak_f32 v48, v37, v51, 0xc09de9e6
	v_mul_f32_e32 v49, v52, v53
	v_mul_f32_e32 v51, v55, v56
	v_fmaak_f32 v52, v39, v57, 0xc09de9e6
	v_mul_f32_e32 v53, v58, v59
	v_mul_f32_e32 v55, v61, v62
	v_mul_f32_e32 v57, v64, v65
	v_fmac_f32_e32 v43, 0x40490fdb, v2
	v_and_b32_e32 v67, 1, v26
	v_and_b32_e32 v68, 1, v27
	v_and_b32_e32 v69, 1, v28
	v_and_b32_e32 v70, 1, v29
	v_and_b32_e32 v71, 1, v30
	v_and_b32_e32 v72, 1, v31
	v_and_b32_e32 v73, 1, v32
	v_fmaak_f32 v50, v38, v54, 0xc09de9e6
	v_fmaak_f32 v54, v40, v60, 0xc09de9e6
	v_fmaak_f32 v56, v41, v63, 0xc09de9e6
	v_fma_f32 v33, v33, v42, 1.0
	v_fmac_f32_e32 v45, 0x40490fdb, v13
	v_fmac_f32_e32 v47, 0x40490fdb, v20
	v_fmac_f32_e32 v49, 0x40490fdb, v21
	v_fmac_f32_e32 v51, 0x40490fdb, v22
	v_fmac_f32_e32 v53, 0x40490fdb, v23
	v_fmac_f32_e32 v55, 0x40490fdb, v24
	v_fmac_f32_e32 v57, 0x40490fdb, v25
	v_xor_b32_e32 v25, 0x80000000, v43
	v_cmp_eq_u32_e32 vcc, 0, v66
	v_lshlrev_b32_e32 v34, 30, v34
	v_fma_f32 v2, v35, v44, 1.0
	v_fma_f32 v13, v36, v46, 1.0
	v_fma_f32 v20, v37, v48, 1.0
	v_fma_f32 v21, v38, v50, 1.0
	v_fma_f32 v22, v39, v52, 1.0
	v_fma_f32 v23, v40, v54, 1.0
	v_fma_f32 v24, v41, v56, 1.0
	v_xor_b32_e32 v35, 0x80000000, v45
	v_cmp_eq_u32_e64 s[0:1], 0, v67
	v_xor_b32_e32 v36, 0x80000000, v47
	v_cmp_eq_u32_e64 s[4:5], 0, v68
	v_xor_b32_e32 v37, 0x80000000, v49
	v_cmp_eq_u32_e64 s[6:7], 0, v69
	v_xor_b32_e32 v38, 0x80000000, v51
	v_cmp_eq_u32_e64 s[8:9], 0, v70
	v_xor_b32_e32 v39, 0x80000000, v53
	v_cmp_eq_u32_e64 s[10:11], 0, v71
	v_xor_b32_e32 v40, 0x80000000, v55
	v_xor_b32_e32 v41, 0x80000000, v57
	v_cmp_eq_u32_e64 s[12:13], 0, v73
	v_cndmask_b32_e32 v25, v25, v33, vcc
	v_cndmask_b32_e32 v33, v33, v43, vcc
	v_cmp_eq_u32_e32 vcc, 0, v72
	v_lshlrev_b32_e32 v26, 30, v26
	v_lshlrev_b32_e32 v27, 30, v27
	v_lshlrev_b32_e32 v28, 30, v28
	v_lshlrev_b32_e32 v29, 30, v29
	v_lshlrev_b32_e32 v30, 30, v30
	v_lshlrev_b32_e32 v31, 30, v31
	v_lshlrev_b32_e32 v32, 30, v32
	v_cndmask_b32_e64 v35, v35, v2, s[0:1]
	v_cndmask_b32_e64 v2, v2, v45, s[0:1]
	v_cndmask_b32_e64 v36, v36, v13, s[4:5]
	v_cndmask_b32_e64 v13, v13, v47, s[4:5]
	v_cndmask_b32_e64 v37, v37, v20, s[6:7]
	v_cndmask_b32_e64 v20, v20, v49, s[6:7]
	v_cndmask_b32_e64 v38, v38, v21, s[8:9]
	v_cndmask_b32_e64 v21, v21, v51, s[8:9]
	v_cndmask_b32_e64 v39, v39, v22, s[10:11]
	v_cndmask_b32_e64 v22, v22, v53, s[10:11]
	v_cndmask_b32_e32 v40, v40, v23, vcc
	v_cndmask_b32_e32 v23, v23, v55, vcc
	v_cndmask_b32_e64 v41, v41, v24, s[12:13]
	v_cndmask_b32_e64 v24, v24, v57, s[12:13]
	v_bitop3_b32 v25, v25, v34, s26 bitop3:0x78
	v_cmp_lg_f32_e32 vcc, s25, v15
	v_bitop3_b32 v15, v33, v34, s26 bitop3:0x78
	v_bitop3_b32 v33, v35, v26, s26 bitop3:0x78
	v_cmp_lg_f32_e64 s[0:1], s25, v14
	v_bitop3_b32 v2, v2, v26, s26 bitop3:0x78
	v_bitop3_b32 v14, v36, v27, s26 bitop3:0x78
	v_cmp_lg_f32_e64 s[4:5], s25, v17
	v_bitop3_b32 v13, v13, v27, s26 bitop3:0x78
	v_bitop3_b32 v17, v37, v28, s26 bitop3:0x78
	v_cmp_lg_f32_e64 s[6:7], s25, v16
	v_bitop3_b32 v16, v20, v28, s26 bitop3:0x78
	v_bitop3_b32 v20, v38, v29, s26 bitop3:0x78
	v_cmp_lg_f32_e64 s[8:9], s25, v19
	v_bitop3_b32 v19, v21, v29, s26 bitop3:0x78
	v_bitop3_b32 v21, v39, v30, s26 bitop3:0x78
	v_cmp_lg_f32_e64 s[10:11], s25, v18
	v_bitop3_b32 v18, v22, v30, s26 bitop3:0x78
	v_bitop3_b32 v22, v40, v31, s26 bitop3:0x78
	v_bitop3_b32 v23, v23, v31, s26 bitop3:0x78
	v_bitop3_b32 v26, v41, v32, s26 bitop3:0x78
	v_cmp_lg_f32_e64 s[12:13], s25, v6
	v_bitop3_b32 v6, v24, v32, s26 bitop3:0x78
	v_cndmask_b32_e32 v24, v12, v25, vcc
	v_cndmask_b32_e32 v15, v12, v15, vcc
	v_cmp_lg_f32_e32 vcc, s25, v7
	v_cndmask_b32_e64 v25, v12, v33, s[0:1]
	v_cndmask_b32_e64 v2, v12, v2, s[0:1]
	v_cndmask_b32_e64 v14, v12, v14, s[4:5]
	v_cndmask_b32_e64 v13, v12, v13, s[4:5]
	v_cndmask_b32_e64 v17, v12, v17, s[6:7]
	v_cndmask_b32_e64 v16, v12, v16, s[6:7]
	v_cndmask_b32_e64 v20, v12, v20, s[8:9]
	v_cndmask_b32_e64 v19, v12, v19, s[8:9]
	v_cndmask_b32_e64 v21, v12, v21, s[10:11]
	v_cndmask_b32_e64 v18, v12, v18, s[10:11]
	v_cndmask_b32_e32 v7, v12, v22, vcc
	v_cndmask_b32_e32 v22, v12, v23, vcc
	v_cndmask_b32_e64 v23, v12, v26, s[12:13]
	v_cndmask_b32_e64 v6, v12, v6, s[12:13]
	v_add_u32_e32 v8, s21, v8
	v_cmp_lt_i32_e32 vcc, s27, v8
	v_add_u32_e32 v9, s22, v9
	s_or_b64 s[18:19], vcc, s[18:19]
	v_mul_f32_e32 v7, 0x3cb504f3, v7
	v_mul_f32_e32 v23, 0x3cb504f3, v23
	v_mul_f32_e32 v24, 0x3cb504f3, v24
	v_mul_f32_e32 v25, 0x3cb504f3, v25
	v_mul_f32_e32 v14, 0x3cb504f3, v14
	v_mul_f32_e32 v17, 0x3cb504f3, v17
	v_mul_f32_e32 v20, 0x3cb504f3, v20
	v_mul_f32_e32 v21, 0x3cb504f3, v21
	v_mul_f32_e32 v22, 0x3cb504f3, v22
	v_mul_f32_e32 v6, 0x3cb504f3, v6
	v_mul_f32_e32 v15, 0x3cb504f3, v15
	v_mul_f32_e32 v2, 0x3cb504f3, v2
	v_mul_f32_e32 v13, 0x3cb504f3, v13
	v_mul_f32_e32 v16, 0x3cb504f3, v16
	v_mul_f32_e32 v19, 0x3cb504f3, v19
	v_mul_f32_e32 v18, 0x3cb504f3, v18
	v_cvt_pk_bf16_f32 v26, v7, v23
	v_cvt_pk_bf16_f32 v27, v24, v25
	v_cvt_pk_bf16_f32 v28, v14, v17
	v_cvt_pk_bf16_f32 v29, v20, v21
	v_cvt_pk_bf16_f32 v30, v22, v6
	v_cvt_pk_bf16_f32 v31, v15, v2
	v_cvt_pk_bf16_f32 v32, v13, v16
	v_cvt_pk_bf16_f32 v33, v19, v18
	v_add_co_u32_e32 v34, vcc, 0x800000, v4
	s_nop 0
	v_addc_co_u32_e32 v35, vcc, 0, v5, vcc
	global_store_dwordx4 v[4:5], v[26:29], off
	global_store_dwordx4 v[34:35], v[30:33], off
	s_andn2_b64 exec, exec, s[18:19]
	s_cbranch_execnz .LBB0_112
